# phase-0 row loop: next iteration's 8 row loads prefetched into a second register bank, counted wait vmcnt(8)
# speedup vs baseline: 1.0015x; 1.0015x over previous
; __device__ __forceinline__ int otid() { int t = threadIdx.x; asm volatile("" : "+v"(t)); return t; }
; __device__ __forceinline__ int obid() { int t = blockIdx.x; asm volatile("" : "+s"(t)); return t; }
; template <bool FINAL>
; __device__ void phase_norm(const float* __restrict__ x, const float* __restrict__ g, bf16_t* __restrict__ xb, float* __restrict__ ss_out, float* __restrict__ outf, int b0, int nb, int rbeg, int rend) {
;     const int tid_ = otid(), lane = tid_ & 63, wid = tid_ >> 6; const int bq = obid() - b0;
;     if (bq < 0) return;
;     f32x4 gv[4];
; #pragma unroll
;     for (int i = 0; i < 4; ++i) gv[i] = FINAL ? *(const f32x4*)(g + (lane + 64 * i) * 4) : (f32x4){1.f, 1.f, 1.f, 1.f};
;     for (int row0 = rbeg + bq * 8 + wid; row0 < rend; row0 += nb * 16) {
;         const int row1 = row0 + nb * 8; const bool has1 = row1 < rend;
;         const float* xr0 = x + (size_t)row0 * 1024; const float* xr1 = x + (size_t)(has1 ? row1 : row0) * 1024; f32x4 v[4], u[4]; float ss = 0.f, st = 0.f;
; #pragma unroll
;         for (int i = 0; i < 4; ++i) { v[i] = *(const f32x4*)(xr0 + (lane + 64 * i) * 4); u[i] = *(const f32x4*)(xr1 + (lane + 64 * i) * 4); }
.LBB0_891:
	s_or_b64 exec, exec, s[6:7]
	v_mov_b32_e32 v0, v191
	s_mov_b32 s4, s2
	s_barrier
	s_cmp_lt_i32 s4, 0
	s_cbranch_scc1 .LBB0_902
	v_ashrrev_i32_e32 v1, 6, v0
	s_lshl_b32 s4, s4, 3
	v_add_u32_e32 v32, s4, v1
	s_mov_b32 s4, 0xa000
	v_cmp_gt_i32_e32 vcc, s4, v32
	s_and_saveexec_b64 s[4:5], vcc
	s_cbranch_execz .LBB0_901
	v_and_b32_e32 v1, 64, v226
	v_add_u32_e32 v2, 64, v1
	v_xor_b32_e32 v3, 32, v226
	v_cmp_lt_i32_e32 vcc, v3, v2
	s_load_dwordx2 s[0:1], s[0:1], 0x0
	v_and_b32_e32 v6, 63, v0
	v_cndmask_b32_e32 v3, v226, v3, vcc
	v_lshlrev_b32_e32 v46, 2, v3
	v_xor_b32_e32 v3, 16, v226
	v_cmp_lt_i32_e32 vcc, v3, v2
	v_ashrrev_i32_e32 v33, 31, v32
	v_lshlrev_b32_e32 v0, 2, v6
	v_cndmask_b32_e32 v3, v226, v3, vcc
	v_lshlrev_b32_e32 v47, 2, v3
	v_xor_b32_e32 v3, 8, v226
	v_cmp_lt_i32_e32 vcc, v3, v2
	v_mov_b32_e32 v1, v184
	v_lshlrev_b64 v[4:5], 6, v[32:33]
	v_cndmask_b32_e32 v3, v226, v3, vcc
	v_lshlrev_b32_e32 v48, 2, v3
	v_xor_b32_e32 v3, 4, v226
	v_cmp_lt_i32_e32 vcc, v3, v2
	v_lshl_add_u64 v[4:5], v[4:5], 0, v[0:1]
	s_mov_b64 s[6:7], 0x3e600000
	v_cndmask_b32_e32 v3, v226, v3, vcc
	v_lshlrev_b32_e32 v49, 2, v3
	v_xor_b32_e32 v3, 2, v226
	v_cmp_lt_i32_e32 vcc, v3, v2
	v_lshl_add_u64 v[36:37], v[4:5], 0, s[6:7]
	v_add_u32_e32 v4, 0x400, v32
	v_cndmask_b32_e32 v3, v226, v3, vcc
	v_lshlrev_b32_e32 v50, 2, v3
	v_xor_b32_e32 v3, 1, v226
	v_cmp_lt_i32_e32 vcc, v3, v2
	v_cmp_gt_u32_e64 s[40:41], 16, v6
	v_cmp_eq_u32_e64 s[42:43], 0, v6
	v_cndmask_b32_e32 v2, v226, v3, vcc
	v_lshlrev_b32_e32 v51, 2, v2
	v_lshlrev_b32_e32 v2, 4, v6
	v_mov_b32_e32 v3, v184
	s_waitcnt lgkmcnt(0)
	v_lshl_add_u64 v[34:35], s[0:1], 0, v[2:3]
	v_lshlrev_b32_e32 v3, 3, v6
	v_ashrrev_i32_e32 v5, 31, v4
	v_lshlrev_b64 v[6:7], 12, v[32:33]
	v_lshlrev_b64 v[38:39], 11, v[32:33]
	v_lshlrev_b64 v[40:41], 11, v[4:5]
	v_or_b32_e32 v6, v6, v2
	v_or_b32_e32 v38, v38, v3
	v_or_b32_e32 v40, v40, v3
	v_lshl_add_u64 v[2:3], s[0:1], 0, v[6:7]
	s_mov_b64 s[0:1], 0xc00
	v_lshl_add_u64 v[42:43], v[2:3], 0, s[0:1]
	v_lshlrev_b64 v[2:3], 6, v[4:5]
	v_lshl_add_u64 v[0:1], v[2:3], 0, v[0:1]
	v_lshl_add_u64 v[44:45], v[0:1], 0, s[6:7]
	s_mov_b64 s[0:1], 0
	global_load_dwordx4 v[88:91], v[42:43], off offset:-3072
	global_load_dwordx4 v[84:87], v[42:43], off offset:-2048
	global_load_dwordx4 v[80:83], v[42:43], off offset:-1024
	global_load_dwordx4 v[76:79], v[42:43], off
	v_add_u32_e32 v95, 0x400, v32
	v_cmp_gt_i32_e32 vcc, 0x9c00, v32
	s_nop 1
	v_cndmask_b32_e32 v94, v32, v95, vcc
	v_ashrrev_i32_e32 v95, 31, v94
	v_lshlrev_b64 v[94:95], 12, v[94:95]
	v_lshl_add_u64 v[94:95], v[34:35], 0, v[94:95]
	global_load_dwordx4 v[72:75], v[94:95], off
	global_load_dwordx4 v[68:71], v[94:95], off offset:1024
	global_load_dwordx4 v[64:67], v[94:95], off offset:2048
	global_load_dwordx4 v[60:63], v[94:95], off offset:3072
	s_waitcnt vmcnt(0)
	s_branch .LBB0_896

; __device__ __forceinline__ unsigned pack2(float lo, float hi) { const f32x2_t v = {lo, hi}; const bf16x2_t b = __builtin_convertvector(v, bf16x2_t); return __builtin_bit_cast(unsigned, b); }
; template <bool FINAL>
; __device__ void phase_norm(const float* __restrict__ x, const float* __restrict__ g, bf16_t* __restrict__ xb, float* __restrict__ ss_out, float* __restrict__ outf, int b0, int nb, int rbeg, int rend) {
;     ...
;     for (int row0 = rbeg + bq * 8 + wid; row0 < rend; row0 += nb * 16) {
;         const int row1 = row0 + nb * 8; const bool has1 = row1 < rend;
;         const float* xr0 = x + (size_t)row0 * 1024; const float* xr1 = x + (size_t)(has1 ? row1 : row0) * 1024; f32x4 v[4], u[4]; float ss = 0.f, st = 0.f;
; #pragma unroll
;         for (int i = 0; i < 4; ++i) { v[i] = *(const f32x4*)(xr0 + (lane + 64 * i) * 4); u[i] = *(const f32x4*)(xr1 + (lane + 64 * i) * 4); }
; #pragma unroll
;         for (int i = 0; i < 4; ++i) { ss += v[i][0] * v[i][0] + v[i][1] * v[i][1] + v[i][2] * v[i][2] + v[i][3] * v[i][3]; st += u[i][0] * u[i][0] + u[i][1] * u[i][1] + u[i][2] * u[i][2] + u[i][3] * u[i][3]; }
; #pragma unroll
;         for (int o = 32; o > 0; o >>= 1) { ss += __shfl_xor(ss, o); st += __shfl_xor(st, o); }
; #pragma unroll
;         for (int rr = 0; rr < 2; ++rr) { if (rr == 1 && !has1) break; const int row = rr ? row1 : row0; const float sv = rr ? st : ss;
;             if (FINAL) { const float rstd = rsqrtf(sv * (1.0f / 1024.0f) + 1e-6f);
; #pragma unroll
;                 for (int i = 0; i < 4; ++i) *(f32x4*)(outf + (size_t)row * 1024 + (lane + 64 * i) * 4) = (rr ? u[i] : v[i]) * rstd * gv[i]; }
;             else { if (lane < 16) ss_out[(size_t)row * 16 + lane] = lane == 0 ? sv : 0.f;
; #pragma unroll
;                 for (int i = 0; i < 4; ++i) { const f32x4 y = rr ? u[i] : v[i]; uint2 w; w.x = pack2(y[0], y[1]); w.y = pack2(y[2], y[3]); *(uint2*)(xb + (size_t)row * 1024 + (lane + 64 * i) * 4) = w; } } }
.LBB0_896:
	s_mov_b32 s6, 0x9c00
	v_add_u32_e32 v0, 0x400, v32
	v_cmp_gt_i32_e64 s[44:45], s6, v32
	v_cndmask_b32_e64 v0, v32, v0, s[44:45]
	v_ashrrev_i32_e32 v1, 31, v0
	v_lshlrev_b64 v[0:1], 12, v[0:1]
	v_lshl_add_u64 v[0:1], v[34:35], 0, v[0:1]
	s_nop 0
	s_waitcnt vmcnt(8)
	v_mov_b64_e32 v[28:29], v[88:89]
	v_mov_b64_e32 v[30:31], v[90:91]
	v_mov_b64_e32 v[24:25], v[84:85]
	v_mov_b64_e32 v[26:27], v[86:87]
	v_mov_b64_e32 v[20:21], v[80:81]
	v_mov_b64_e32 v[22:23], v[82:83]
	v_mov_b64_e32 v[16:17], v[76:77]
	v_mov_b64_e32 v[18:19], v[78:79]
	v_mov_b64_e32 v[12:13], v[72:73]
	v_mov_b64_e32 v[14:15], v[74:75]
	v_mov_b64_e32 v[8:9], v[68:69]
	v_mov_b64_e32 v[10:11], v[70:71]
	v_mov_b64_e32 v[4:5], v[64:65]
	v_mov_b64_e32 v[6:7], v[66:67]
	v_mov_b64_e32 v[0:1], v[60:61]
	v_mov_b64_e32 v[2:3], v[62:63]
	v_cmp_gt_i32_e32 vcc, 0x9800, v32
	s_and_saveexec_b64 s[8:9], vcc
	v_mov_b32_e32 v92, 0x800000
	v_mov_b32_e32 v93, 0
	v_lshl_add_u64 v[92:93], v[42:43], 0, v[92:93]
	global_load_dwordx4 v[88:91], v[92:93], off offset:-3072
	global_load_dwordx4 v[84:87], v[92:93], off offset:-2048
	global_load_dwordx4 v[80:83], v[92:93], off offset:-1024
	global_load_dwordx4 v[76:79], v[92:93], off
	v_add_u32_e32 v94, 0x800, v32
	v_add_u32_e32 v95, 0xc00, v32
	v_cmp_gt_i32_e32 vcc, 0x9c00, v94
	s_nop 1
	v_cndmask_b32_e32 v94, v94, v95, vcc
	v_ashrrev_i32_e32 v95, 31, v94
	v_lshlrev_b64 v[94:95], 12, v[94:95]
	v_lshl_add_u64 v[94:95], v[34:35], 0, v[94:95]
	global_load_dwordx4 v[72:75], v[94:95], off
	global_load_dwordx4 v[68:71], v[94:95], off offset:1024
	global_load_dwordx4 v[64:67], v[94:95], off offset:2048
	global_load_dwordx4 v[60:63], v[94:95], off offset:3072
	s_or_b64 exec, exec, s[8:9]
	s_nop 0
	v_mul_f32_e32 v33, v29, v29
	s_waitcnt lgkmcnt(0)
	v_mul_f32_e32 v52, v25, v25
	s_nop 0
	v_mul_f32_e32 v53, v21, v21
	v_fmac_f32_e32 v33, v28, v28
	v_fmac_f32_e32 v52, v24, v24
	v_fmac_f32_e32 v53, v20, v20
	v_fmac_f32_e32 v33, v30, v30
	v_fmac_f32_e32 v52, v26, v26
	v_fmac_f32_e32 v53, v22, v22
	v_fmac_f32_e32 v33, v31, v31
	v_fmac_f32_e32 v52, v27, v27
	v_fmac_f32_e32 v53, v23, v23
	v_add_f32_e32 v33, v33, v52
	s_nop 0
	v_mul_f32_e32 v52, v13, v13
	s_nop 0
	v_mul_f32_e32 v55, v9, v9
	v_add_f32_e32 v33, v33, v53
	s_nop 0
	v_mul_f32_e32 v53, v5, v5
	v_fmac_f32_e32 v52, v12, v12
	v_fmac_f32_e32 v55, v8, v8
	v_mul_f32_e32 v54, v17, v17
	s_nop 0
	v_mul_f32_e32 v56, v1, v1
	v_fmac_f32_e32 v53, v4, v4
	v_fmac_f32_e32 v52, v14, v14
	v_fmac_f32_e32 v55, v10, v10
	v_fmac_f32_e32 v54, v16, v16
	v_fmac_f32_e32 v56, v0, v0
	v_fmac_f32_e32 v53, v6, v6
	v_fmac_f32_e32 v52, v15, v15
	v_fmac_f32_e32 v55, v11, v11
	v_fmac_f32_e32 v54, v18, v18
	v_fmac_f32_e32 v56, v2, v2
	v_fmac_f32_e32 v53, v7, v7
	v_add_f32_e32 v52, v52, v55
	v_fmac_f32_e32 v54, v19, v19
	v_fmac_f32_e32 v56, v3, v3
	v_add_f32_e32 v52, v52, v53
	v_add_f32_e32 v33, v33, v54
	v_add_f32_e32 v52, v52, v56
	ds_bpermute_b32 v54, v46, v33
	ds_bpermute_b32 v53, v46, v52
	s_waitcnt lgkmcnt(1)
	v_add_f32_e32 v33, v33, v54
	s_waitcnt lgkmcnt(0)
	v_add_f32_e32 v52, v52, v53
	ds_bpermute_b32 v54, v47, v33
	ds_bpermute_b32 v53, v47, v52
	s_waitcnt lgkmcnt(1)
	v_add_f32_e32 v33, v33, v54
	s_waitcnt lgkmcnt(0)
	v_add_f32_e32 v52, v52, v53
	ds_bpermute_b32 v54, v48, v33
	ds_bpermute_b32 v53, v48, v52
	s_waitcnt lgkmcnt(1)
	v_add_f32_e32 v33, v33, v54
	s_waitcnt lgkmcnt(0)
	v_add_f32_e32 v52, v52, v53
	ds_bpermute_b32 v54, v49, v33
	ds_bpermute_b32 v53, v49, v52
	s_waitcnt lgkmcnt(1)
	v_add_f32_e32 v33, v33, v54
	s_waitcnt lgkmcnt(0)
	v_add_f32_e32 v52, v52, v53
	ds_bpermute_b32 v54, v50, v33
	ds_bpermute_b32 v55, v50, v52
	s_waitcnt lgkmcnt(1)
	v_add_f32_e32 v53, v33, v54
	s_waitcnt lgkmcnt(0)
	v_add_f32_e32 v33, v52, v55
	ds_bpermute_b32 v54, v51, v53
	ds_bpermute_b32 v52, v51, v33
	s_and_saveexec_b64 s[6:7], s[40:41]
	s_cbranch_execz .LBB0_898
	s_waitcnt lgkmcnt(1)
	v_add_f32_e32 v53, v53, v54
	v_lshl_add_u64 v[56:57], s[94:95], 0, v[36:37]
	v_cndmask_b32_e64 v53, 0, v53, s[42:43]
	global_store_dword v[56:57], v53, off
